# P1 static order: round i takes the unit of CU (c+64i) mod 256 so every CU gets 5 units of each epilogue kind (was: 128 CUs with all q/k-norm+rotary epilogues)
# baseline (speedup 1.0000x reference)
;     __host__ __device__ bool next(int i, Unit& u) const {
;         const long L = (long)i * G + c; if (L >= nwg) return false;
;         int wgid = (int)L; { const int q = nwg / NXCD, r = nwg % NXCD, xcd = wgid % NXCD, off = wgid / NXCD; wgid = (xcd < r ? xcd * (q + 1) : r * (q + 1) + (xcd - r) * q) + off; }
;         const int nig = WGM * nN, gid = wgid / nig, fm = gid * WGM, gsz = (nM - fm) < WGM ? (nM - fm) : WGM;
;         u.pm = fm + ((wgid % nig) % gsz); u.pn = (wgid % nig) / gsz; return true;
.LBB0_159:
	s_add_i32 s76, s76, 1
	s_mul_i32 s0, s76, s80
	s_mul_hi_u32 s1, s76, s3
	s_add_i32 s1, s1, s0
	s_mul_i32 s0, s76, s3
	s_lshl_b32 s94, s76, 6
	s_add_i32 s94, s94, s2
	s_and_b32 s94, s94, 0xff
	s_cmp_eq_u32 s3, 0x100
	s_cselect_b32 s94, s94, s2
	s_add_u32 s42, s0, s94
	s_addc_u32 s43, s1, s81
	v_cmp_gt_i64_e32 vcc, s[42:43], v[170:171]
	v_cmp_lt_i64_e64 s[0:1], s[42:43], v[168:169]
	s_cbranch_vccnz .LBB0_161
	s_ashr_i32 s5, s42, 31
	s_lshr_b32 s5, s5, 29
	s_add_i32 s5, s42, s5
	s_ashr_i32 s26, s5, 3
	s_and_b32 s5, s5, -8
	s_sub_i32 s5, s42, s5
	s_cmp_lt_i32 s5, 0
	s_cselect_b32 s27, s84, 0x280
	s_mul_i32 s5, s5, s27
	s_add_i32 s5, s5, s26
	s_ashr_i32 s26, s5, 31
	s_lshr_b32 s26, s26, 26
	s_add_i32 s26, s5, s26
	s_ashr_i32 s27, s26, 6
	s_lshl_b32 s27, s27, 2
	s_sub_i32 s34, 0x140, s27
	s_min_i32 s34, s34, 4
	s_abs_i32 s35, s34
	v_cvt_f32_u32_e32 v2, s35
	s_sub_i32 s41, 0, s35
	s_andn2_b32 s26, s26, 63
	s_sub_i32 s5, s5, s26
	v_rcp_iflag_f32_e32 v2, v2
	s_abs_i32 s26, s5
	s_xor_b32 s40, s5, s34
	s_ashr_i32 s40, s40, 31
	v_mul_f32_e32 v2, 0x4f7ffffe, v2
	v_cvt_u32_f32_e32 v2, v2
	s_nop 0
	v_readfirstlane_b32 s42, v2
	s_mul_i32 s41, s41, s42
	s_mul_hi_u32 s41, s42, s41
	s_add_i32 s42, s42, s41
	s_mul_hi_u32 s41, s26, s42
	s_mul_i32 s42, s41, s35
	s_sub_i32 s26, s26, s42
	s_add_i32 s43, s41, 1
	s_sub_i32 s42, s26, s35
	s_cmp_ge_u32 s26, s35
	s_cselect_b32 s41, s43, s41
	s_cselect_b32 s26, s42, s26
	s_add_i32 s42, s41, 1
	s_cmp_ge_u32 s26, s35
	s_cselect_b32 s26, s42, s41
	s_xor_b32 s26, s26, s40
	s_sub_i32 s26, s26, s40
	s_mul_i32 s34, s26, s34
	s_sub_i32 s5, s5, s34
	s_add_i32 s40, s27, s5
